# P2 AP pass: L2 prefetch (one dummy dword per 64 B) of each wave's next x row, on top of v27
# baseline (speedup 1.0000x reference)
; DI u32x4 pack8(const float* v) { u32x4 w; w.x = pk2(v[0], v[1]); w.y = pk2(v[2], v[3]); w.z = pk2(v[4], v[5]); w.w = pk2(v[6], v[7]); return w; }
; DI float shx(float v, int lane, int m) { return __builtin_bit_cast(float, __builtin_amdgcn_ds_bpermute((lane ^ m) << 2, __builtin_bit_cast(int, v))); }
; #define PIN(i) gptr(P.in[i])
; __global__ void __launch_bounds__(512, 2) mega(Params P) {
;     ...
;         for (int row = (bid - 32) * 8 + w; row < MT; row += (G - 32) * 8) {
;             int mb, pos, kvrow; row_info(row, mb, pos, kvrow);
;             const float* xr = row < MP ? PIN(I_XP) + (size_t)row * 1024 : PIN(I_XS) + (size_t)(row - MP) * 1024;
;             const float* sc1 = MOD + (size_t)mb * 6144 + 1024;
;             float s = 0.f;
; #pragma unroll
;             for (int half = 0; half < 2; ++half) {
;                 const int c = half * 512 + lane * 8;
;                 float v[8];
; #pragma unroll
;                 for (int q = 0; q < 2; ++q) {
;                     const f32x4 x = *(const f32x4*)(xr + c + 4 * q), g = *(const f32x4*)(PIN(I_GN1) + c + 4 * q), sc = *(const f32x4*)(sc1 + c + 4 * q);
; #pragma unroll
;                     for (int j = 0; j < 4; ++j) { s += x[j] * x[j]; v[4 * q + j] = x[j] * g[j] * (1.f + sc[j]); }
;                 }
;                 *(u32x4*)(AP + (size_t)row * 1024 + c) = pack8(v);
;             }
; #pragma unroll
;             for (int o = 32; o >= 1; o >>= 1) s += shx(s, lane, o);
;             if (lane < 16) SSQ[(size_t)row * 16 + lane] = lane == 0 ? s : 0.f;
;         }
.LBB0_277:
	v_cmp_gt_i32_e64 s[2:3], s14, v0
	v_cmp_lt_i32_e64 s[4:5], s22, v0
	v_add_u32_e32 v2, 0xffffc000, v0
	v_mov_b64_e32 v[18:19], v[0:1]
	s_waitcnt lgkmcnt(0)
	v_mov_b64_e32 v[20:21], v[10:11]
	s_and_saveexec_b64 s[18:19], s[4:5]
	v_lshlrev_b64 v[18:19], 12, v[2:3]
	v_lshl_add_u64 v[20:21], s[58:59], 0, v[18:19]
	v_mov_b32_e32 v18, v0
	v_mov_b32_e32 v19, v3
	s_or_b64 exec, exec, s[18:19]
	v_lshrrev_b32_e32 v2, 6, v2
	v_ashrrev_i32_e32 v28, 11, v0
	v_add_u32_e32 v2, 8, v2
	v_cndmask_b32_e64 v2, v2, v28, s[2:3]
	v_mad_i64_i32 v[44:45], s[2:3], v2, s23, v[12:13]
	v_lshl_add_u64 v[52:53], v[44:45], 0, s[16:17]
	v_lshl_add_u64 v[20:21], v[20:21], 0, v[14:15]
	v_lshl_add_u64 v[48:49], v[52:53], 0, v[14:15]
	global_load_dwordx4 v[28:31], v[20:21], off offset:16
	global_load_dwordx4 v[32:35], v[20:21], off
	global_load_dwordx4 v[36:39], v[6:7], off offset:16
	global_load_dwordx4 v[40:43], v[6:7], off
	global_load_dwordx4 v[44:47], v[48:49], off
	s_nop 0
	global_load_dwordx4 v[48:51], v[48:49], off offset:16
	v_lshl_add_u64 v[72:73], v[0:1], 0, s[8:9]
	v_cmp_gt_i32_e64 s[28:29], s14, v72
	s_and_saveexec_b64 s[30:31], s[28:29]
	v_lshl_add_u64 v[74:75], v[10:11], 0, s[10:11]
	v_lshlrev_b32_e32 v72, 1, v14
	v_mov_b32_e32 v73, 0
	v_lshl_add_u64 v[74:75], v[74:75], 0, v[72:73]
	global_load_dword v76, v[74:75], off
	s_or_b64 exec, exec, s[30:31]
	v_lshlrev_b64 v[54:55], 11, v[18:19]
	v_lshl_add_u64 v[60:61], v[8:9], 0, v[54:55]
	s_waitcnt vmcnt(0)
	v_mul_f32_e32 v2, v33, v33
	v_pk_mul_f32 v[38:39], v[30:31], v[38:39]
	v_pk_mul_f32 v[42:43], v[34:35], v[42:43]
	v_pk_mul_f32 v[40:41], v[32:33], v[40:41]
	v_pk_mul_f32 v[36:37], v[28:29], v[36:37]
	v_pk_add_f32 v[44:45], v[44:45], 1.0 op_sel_hi:[1,0]
	v_pk_add_f32 v[46:47], v[46:47], 1.0 op_sel_hi:[1,0]
	v_pk_add_f32 v[48:49], v[48:49], 1.0 op_sel_hi:[1,0]
	v_pk_add_f32 v[50:51], v[50:51], 1.0 op_sel_hi:[1,0]
	v_pk_mul_f32 v[40:41], v[40:41], v[44:45]
	v_pk_mul_f32 v[42:43], v[42:43], v[46:47]
	v_pk_mul_f32 v[44:45], v[36:37], v[48:49]
	v_pk_mul_f32 v[46:47], v[38:39], v[50:51]
	v_cvt_pk_bf16_f32 v36, v40, v41
	v_cvt_pk_bf16_f32 v37, v42, v43
	v_cvt_pk_bf16_f32 v38, v44, v45
	v_cvt_pk_bf16_f32 v39, v46, v47
	global_store_dwordx4 v[60:61], v[36:39], off
	global_load_dwordx4 v[36:39], v[20:21], off offset:2048
	s_nop 0
	global_load_dwordx4 v[40:43], v[20:21], off offset:2064
	global_load_dwordx4 v[44:47], v[6:7], off offset:2048
	v_lshl_add_u64 v[20:21], v[52:53], 0, v[16:17]
	global_load_dwordx4 v[48:51], v[20:21], off
	global_load_dwordx4 v[52:55], v[6:7], off offset:2064
	global_load_dwordx4 v[56:59], v[20:21], off offset:16
	v_fmac_f32_e32 v2, v32, v32
	v_fmac_f32_e32 v2, v34, v34
	v_fmac_f32_e32 v2, v35, v35
	v_fmac_f32_e32 v2, v28, v28
	v_fmac_f32_e32 v2, v29, v29
	v_fmac_f32_e32 v2, v30, v30
	v_fmac_f32_e32 v2, v31, v31
	s_waitcnt vmcnt(5)
	v_fmac_f32_e32 v2, v36, v36
	v_fmac_f32_e32 v2, v37, v37
	v_fmac_f32_e32 v2, v38, v38
	v_fmac_f32_e32 v2, v39, v39
	s_waitcnt vmcnt(4)
	v_fmac_f32_e32 v2, v40, v40
	v_fmac_f32_e32 v2, v41, v41
	v_fmac_f32_e32 v2, v42, v42
	v_fmac_f32_e32 v2, v43, v43
	ds_bpermute_b32 v20, v22, v2
	s_waitcnt vmcnt(2)
	v_pk_add_f32 v[30:31], v[48:49], 1.0 op_sel_hi:[1,0]
	s_waitcnt vmcnt(0)
	v_pk_add_f32 v[34:35], v[56:57], 1.0 op_sel_hi:[1,0]
	s_waitcnt lgkmcnt(0)
	v_add_f32_e32 v2, v2, v20
	ds_bpermute_b32 v28, v23, v2
	v_pk_mul_f32 v[20:21], v[38:39], v[46:47]
	s_waitcnt lgkmcnt(0)
	v_add_f32_e32 v2, v2, v28
	ds_bpermute_b32 v32, v24, v2
	v_pk_mul_f32 v[28:29], v[36:37], v[44:45]
	s_waitcnt lgkmcnt(0)
	v_add_f32_e32 v2, v2, v32
	ds_bpermute_b32 v36, v25, v2
	v_pk_mul_f32 v[28:29], v[28:29], v[30:31]
	v_pk_add_f32 v[30:31], v[50:51], 1.0 op_sel_hi:[1,0]
	v_pk_mul_f32 v[32:33], v[40:41], v[52:53]
	v_pk_mul_f32 v[30:31], v[20:21], v[30:31]
	s_waitcnt lgkmcnt(0)
	v_add_f32_e32 v2, v2, v36
	ds_bpermute_b32 v36, v26, v2
	v_pk_mul_f32 v[20:21], v[42:43], v[54:55]
	v_pk_mul_f32 v[32:33], v[32:33], v[34:35]
	v_pk_add_f32 v[34:35], v[58:59], 1.0 op_sel_hi:[1,0]
	v_cvt_pk_bf16_f32 v28, v28, v29
	s_waitcnt lgkmcnt(0)
	v_add_f32_e32 v2, v2, v36
	v_pk_mul_f32 v[34:35], v[20:21], v[34:35]
	ds_bpermute_b32 v20, v27, v2
	v_cvt_pk_bf16_f32 v29, v30, v31
	v_cvt_pk_bf16_f32 v30, v32, v33
	v_cvt_pk_bf16_f32 v31, v34, v35
	global_store_dwordx4 v[60:61], v[28:31], off offset:1024
	s_and_saveexec_b64 s[2:3], vcc
	s_cbranch_execz .LBB0_276
	s_waitcnt lgkmcnt(0)
	v_add_f32_e32 v2, v2, v20
	v_lshlrev_b64 v[18:19], 6, v[18:19]
	v_lshl_add_u64 v[18:19], v[4:5], 0, v[18:19]
	v_cndmask_b32_e64 v2, 0, v2, s[0:1]
	global_store_dword v[18:19], v2, off
	s_branch .LBB0_276
